# mix_side pooling: the 15 serialized conditional row loads become 8 prefetched rows plus rolling refills (2 exposed round trips instead of 15)
# speedup vs baseline: 1.0074x; 1.0074x over previous
.LBB7_700:
	v_ashrrev_i32_e32 v2, 2, v151
	v_bfe_u32 v207, v151, 6, 2
	v_and_b32_e32 v0, 56, v205
	v_and_b32_e32 v2, 0xffffffc0, v2
	v_and_b32_e32 v3, 56, v151
	s_movk_i32 s3, 0x7f8
	v_lshl_or_b32 v0, v207, 6, v0
	v_bitop3_b32 v206, v2, s3, v3 bitop3:0xc8
	v_mov_b32_e32 v32, v1
	v_mov_b32_e32 v33, v1
	v_or_b32_e32 v18, v2, v3
	v_lshlrev_b32_e32 v0, 1, v0
	v_cmp_eq_u32_e64 s[40:41], 3, v207
	v_cmp_lt_u32_e32 vcc, 14, v206
	v_mov_b32_e32 v30, v1
	v_mov_b32_e32 v31, v1
	v_mov_b64_e32 v[36:37], v[32:33]
	v_lshl_add_u64 v[20:21], s[44:45], 0, v[0:1]
	s_and_b64 s[4:5], s[40:41], vcc
	v_ashrrev_i32_e32 v19, 31, v18
	v_mov_b64_e32 v[34:35], v[30:31]
	v_lshlrev_b64 v[248:249], 11, v[18:19]
	v_lshl_add_u64 v[248:249], v[20:21], 0, v[248:249]
	v_add_co_u32_e32 v248, vcc, 0xffff9000, v248
	s_nop 1
	v_addc_co_u32_e32 v249, vcc, -1, v249, vcc
	global_load_dwordx4 v[216:219], v[248:249], off offset:-2048
	global_load_dwordx4 v[220:223], v[248:249], off
	global_load_dwordx4 v[224:227], v[248:249], off offset:2048
	v_add_co_u32_e32 v248, vcc, 0x1800, v248
	s_nop 1
	v_addc_co_u32_e32 v249, vcc, 0, v249, vcc
	global_load_dwordx4 v[228:231], v[248:249], off offset:-2048
	global_load_dwordx4 v[232:235], v[248:249], off
	global_load_dwordx4 v[236:239], v[248:249], off offset:2048
	v_add_co_u32_e32 v248, vcc, 0x1800, v248
	s_nop 1
	v_addc_co_u32_e32 v249, vcc, 0, v249, vcc
	global_load_dwordx4 v[240:243], v[248:249], off offset:-2048
	global_load_dwordx4 v[244:247], v[248:249], off
	s_waitcnt vmcnt(0)
	s_and_saveexec_b64 s[12:13], s[4:5]
	s_cbranch_execz .LBB7_702
	v_lshlrev_b64 v[2:3], 11, v[18:19]
	v_lshl_add_u64 v[2:3], v[20:21], 0, v[2:3]
	v_add_co_u32_e32 v2, vcc, 0xffff9000, v2
	s_nop 1
	v_addc_co_u32_e32 v3, vcc, -1, v3, vcc
	v_mov_b64_e32 v[2:3], v[216:217]
	v_mov_b64_e32 v[4:5], v[218:219]
	v_lshlrev_b32_e32 v6, 16, v2
	v_and_b32_e32 v7, 0xffff0000, v2
	v_lshlrev_b32_e32 v2, 16, v3
	v_and_b32_e32 v3, 0xffff0000, v3
	v_lshlrev_b32_e32 v8, 16, v4
	v_and_b32_e32 v9, 0xffff0000, v4
	v_lshlrev_b32_e32 v4, 16, v5
	v_and_b32_e32 v5, 0xffff0000, v5
	v_pk_add_f32 v[36:37], v[2:3], 0 op_sel_hi:[1,0]
	v_pk_add_f32 v[34:35], v[6:7], 0 op_sel_hi:[1,0]
	v_pk_add_f32 v[32:33], v[4:5], 0 op_sel_hi:[1,0]
	v_pk_add_f32 v[30:31], v[8:9], 0 op_sel_hi:[1,0]
.LBB7_702:
	s_or_b64 exec, exec, s[12:13]
	global_load_dwordx4 v[216:219], v[248:249], off offset:2048
	v_add_co_u32_e32 v248, vcc, 0x2000, v248
	s_nop 1
	v_addc_co_u32_e32 v249, vcc, 0, v249, vcc
	v_cmp_lt_u32_e32 vcc, 13, v206
	s_and_b64 s[4:5], s[40:41], vcc
	v_mov_b32_e32 v2, 0
	v_mov_b32_e32 v4, 0
	v_mov_b32_e32 v5, 0
	v_mov_b32_e32 v8, 0
	v_mov_b32_e32 v9, 0
	v_mov_b32_e32 v6, 0
	v_mov_b32_e32 v7, 0
	v_mov_b32_e32 v10, 0
	v_mov_b32_e32 v11, 0
	s_and_saveexec_b64 s[12:13], s[4:5]
	s_cbranch_execz .LBB7_704
	v_lshlrev_b64 v[4:5], 11, v[18:19]
	v_lshl_add_u64 v[4:5], v[20:21], 0, v[4:5]
	v_add_co_u32_e32 v4, vcc, 0xffff9000, v4
	s_nop 1
	v_addc_co_u32_e32 v5, vcc, -1, v5, vcc
	v_mov_b64_e32 v[10:11], v[220:221]
	v_mov_b64_e32 v[12:13], v[222:223]
	v_lshlrev_b32_e32 v6, 16, v10
	v_and_b32_e32 v7, 0xffff0000, v10
	v_lshlrev_b32_e32 v10, 16, v11
	v_and_b32_e32 v11, 0xffff0000, v11
	v_lshlrev_b32_e32 v4, 16, v12
	v_and_b32_e32 v5, 0xffff0000, v12
	v_lshlrev_b32_e32 v8, 16, v13
	v_and_b32_e32 v9, 0xffff0000, v13
.LBB7_704:
	s_or_b64 exec, exec, s[12:13]
	global_load_dwordx4 v[220:223], v[248:249], off offset:-4096
	v_cmp_lt_u32_e32 vcc, 12, v206
	s_and_b64 s[4:5], s[40:41], vcc
	v_mov_b32_e32 v3, 0
	v_mov_b32_e32 v14, 0
	v_mov_b32_e32 v15, 0
	v_mov_b32_e32 v12, 0
	v_mov_b32_e32 v13, 0
	v_mov_b32_e32 v16, 0
	v_mov_b32_e32 v17, 0
	s_and_saveexec_b64 s[12:13], s[4:5]
	s_cbranch_execz .LBB7_706
	v_lshlrev_b64 v[2:3], 11, v[18:19]
	v_lshl_add_u64 v[2:3], v[20:21], 0, v[2:3]
	v_add_co_u32_e32 v2, vcc, 0xffffa000, v2
	s_nop 1
	v_addc_co_u32_e32 v3, vcc, -1, v3, vcc
	v_mov_b64_e32 v[22:23], v[224:225]
	v_mov_b64_e32 v[24:25], v[226:227]
	v_lshlrev_b32_e32 v12, 16, v22
	v_and_b32_e32 v13, 0xffff0000, v22
	v_lshlrev_b32_e32 v16, 16, v23
	v_and_b32_e32 v17, 0xffff0000, v23
	v_lshlrev_b32_e32 v2, 16, v24
	v_and_b32_e32 v3, 0xffff0000, v24
	v_lshlrev_b32_e32 v14, 16, v25
	v_and_b32_e32 v15, 0xffff0000, v25
.LBB7_706:
	s_or_b64 exec, exec, s[12:13]
	global_load_dwordx4 v[224:227], v[248:249], off offset:-2048
	v_cmp_lt_u32_e32 vcc, 11, v206
	s_and_b64 s[4:5], s[40:41], vcc
	v_mov_b32_e32 v22, 0
	v_mov_b32_e32 v24, 0
	v_mov_b32_e32 v25, 0
	v_mov_b32_e32 v28, 0
	v_mov_b32_e32 v29, 0
	v_mov_b32_e32 v26, 0
	v_mov_b32_e32 v27, 0
	v_mov_b32_e32 v38, 0
	v_mov_b32_e32 v39, 0
	s_and_saveexec_b64 s[12:13], s[4:5]
	s_cbranch_execz .LBB7_708
	v_lshlrev_b64 v[24:25], 11, v[18:19]
	v_lshl_add_u64 v[24:25], v[20:21], 0, v[24:25]
	v_add_co_u32_e32 v24, vcc, 0xffffa000, v24
	s_nop 1
	v_addc_co_u32_e32 v25, vcc, -1, v25, vcc
	v_mov_b64_e32 v[38:39], v[228:229]
	v_mov_b64_e32 v[40:41], v[230:231]
	v_lshlrev_b32_e32 v26, 16, v38
	v_and_b32_e32 v27, 0xffff0000, v38
	v_lshlrev_b32_e32 v38, 16, v39
	v_and_b32_e32 v39, 0xffff0000, v39
	v_lshlrev_b32_e32 v24, 16, v40
	v_and_b32_e32 v25, 0xffff0000, v40
	v_lshlrev_b32_e32 v28, 16, v41
	v_and_b32_e32 v29, 0xffff0000, v41
.LBB7_708:
	s_or_b64 exec, exec, s[12:13]
	global_load_dwordx4 v[228:231], v[248:249], off
	v_cmp_lt_u32_e32 vcc, 10, v206
	s_and_b64 s[4:5], s[40:41], vcc
	v_mov_b32_e32 v23, 0
	v_mov_b32_e32 v50, 0
	v_mov_b32_e32 v51, 0
	v_mov_b32_e32 v40, 0
	v_mov_b32_e32 v41, 0
	v_mov_b32_e32 v52, 0
	v_mov_b32_e32 v53, 0
	s_and_saveexec_b64 s[12:13], s[4:5]
	s_cbranch_execz .LBB7_710
	v_lshlrev_b64 v[22:23], 11, v[18:19]
	v_lshl_add_u64 v[22:23], v[20:21], 0, v[22:23]
	v_add_co_u32_e32 v22, vcc, 0xffffb000, v22
	s_nop 1
	v_addc_co_u32_e32 v23, vcc, -1, v23, vcc
	v_mov_b64_e32 v[42:43], v[232:233]
	v_mov_b64_e32 v[44:45], v[234:235]
	v_lshlrev_b32_e32 v40, 16, v42
	v_and_b32_e32 v41, 0xffff0000, v42
	v_lshlrev_b32_e32 v52, 16, v43
	v_and_b32_e32 v53, 0xffff0000, v43
	v_lshlrev_b32_e32 v22, 16, v44
	v_and_b32_e32 v23, 0xffff0000, v44
	v_lshlrev_b32_e32 v50, 16, v45
	v_and_b32_e32 v51, 0xffff0000, v45
.LBB7_710:
	s_or_b64 exec, exec, s[12:13]
	global_load_dwordx4 v[232:235], v[248:249], off offset:2048
	v_add_co_u32_e32 v248, vcc, 0x2000, v248
	s_nop 1
	v_addc_co_u32_e32 v249, vcc, 0, v249, vcc
	v_cmp_lt_u32_e32 vcc, 9, v206
	s_and_b64 s[4:5], s[40:41], vcc
	v_mov_b32_e32 v78, 0
	v_mov_b32_e32 v80, 0
	v_mov_b32_e32 v81, 0
	v_mov_b32_e32 v100, 0
	v_mov_b32_e32 v101, 0
	v_mov_b32_e32 v98, 0
	v_mov_b32_e32 v99, 0
	v_mov_b32_e32 v110, 0
	v_mov_b32_e32 v111, 0
	s_and_saveexec_b64 s[12:13], s[4:5]
	s_cbranch_execz .LBB7_712
	v_lshlrev_b64 v[42:43], 11, v[18:19]
	v_lshl_add_u64 v[42:43], v[20:21], 0, v[42:43]
	v_add_co_u32_e32 v42, vcc, 0xffffb000, v42
	s_nop 1
	v_addc_co_u32_e32 v43, vcc, -1, v43, vcc
	v_mov_b64_e32 v[42:43], v[236:237]
	v_mov_b64_e32 v[44:45], v[238:239]
	v_lshlrev_b32_e32 v98, 16, v42
	v_and_b32_e32 v99, 0xffff0000, v42
	v_lshlrev_b32_e32 v110, 16, v43
	v_and_b32_e32 v111, 0xffff0000, v43
	v_lshlrev_b32_e32 v80, 16, v44
	v_and_b32_e32 v81, 0xffff0000, v44
	v_lshlrev_b32_e32 v100, 16, v45
	v_and_b32_e32 v101, 0xffff0000, v45
.LBB7_712:
	s_or_b64 exec, exec, s[12:13]
	global_load_dwordx4 v[236:239], v[248:249], off offset:-4096
	v_cmp_lt_u32_e32 vcc, 8, v206
	s_and_b64 s[4:5], s[40:41], vcc
	v_mov_b32_e32 v79, 0
	v_mov_b32_e32 v114, 0
	v_mov_b32_e32 v115, 0
	v_mov_b32_e32 v112, 0
	v_mov_b32_e32 v113, 0
	v_mov_b32_e32 v116, 0
	v_mov_b32_e32 v117, 0
	s_and_saveexec_b64 s[12:13], s[4:5]
	s_cbranch_execz .LBB7_714
	v_lshlrev_b64 v[42:43], 11, v[18:19]
	v_lshl_add_u64 v[42:43], v[20:21], 0, v[42:43]
	v_add_co_u32_e32 v42, vcc, 0xffffc000, v42
	s_nop 1
	v_addc_co_u32_e32 v43, vcc, -1, v43, vcc
	v_mov_b64_e32 v[42:43], v[240:241]
	v_mov_b64_e32 v[44:45], v[242:243]
	v_lshlrev_b32_e32 v112, 16, v42
	v_and_b32_e32 v113, 0xffff0000, v42
	v_lshlrev_b32_e32 v116, 16, v43
	v_and_b32_e32 v117, 0xffff0000, v43
	v_lshlrev_b32_e32 v78, 16, v44
	v_and_b32_e32 v79, 0xffff0000, v44
	v_lshlrev_b32_e32 v114, 16, v45
	v_and_b32_e32 v115, 0xffff0000, v45
.LBB7_714:
	s_or_b64 exec, exec, s[12:13]
	global_load_dwordx4 v[240:243], v[248:249], off offset:-2048
	v_cmp_lt_u32_e32 vcc, 1, v207
	v_cmp_ne_u32_e64 s[40:41], 0, v206
	s_and_b64 s[12:13], vcc, s[40:41]
	v_mov_b32_e32 v62, 0
	v_mov_b32_e32 v122, 0
	v_mov_b32_e32 v123, 0
	v_mov_b32_e32 v124, 0
	v_mov_b32_e32 v125, 0
	v_mov_b32_e32 v118, 0
	v_mov_b32_e32 v119, 0
	v_mov_b32_e32 v126, 0
	v_mov_b32_e32 v127, 0
	s_and_saveexec_b64 s[14:15], s[12:13]
	s_cbranch_execz .LBB7_716
	v_lshlrev_b64 v[42:43], 11, v[18:19]
	v_lshl_add_u64 v[42:43], v[20:21], 0, v[42:43]
	v_add_co_u32_e32 v42, vcc, 0xffffc000, v42
	s_nop 1
	v_addc_co_u32_e32 v43, vcc, -1, v43, vcc
	v_mov_b64_e32 v[42:43], v[244:245]
	v_mov_b64_e32 v[44:45], v[246:247]
	v_lshlrev_b32_e32 v118, 16, v42
	v_and_b32_e32 v119, 0xffff0000, v42
	v_lshlrev_b32_e32 v126, 16, v43
	v_and_b32_e32 v127, 0xffff0000, v43
	v_lshlrev_b32_e32 v122, 16, v44
	v_and_b32_e32 v123, 0xffff0000, v44
	v_lshlrev_b32_e32 v124, 16, v45
	v_and_b32_e32 v125, 0xffff0000, v45
.LBB7_716:
	s_or_b64 exec, exec, s[14:15]
	v_mov_b32_e32 v63, 0
	v_mov_b32_e32 v64, 0
	v_mov_b32_e32 v65, 0
	v_mov_b32_e32 v68, 0
	v_mov_b32_e32 v69, 0
	v_mov_b32_e32 v70, 0
	v_mov_b32_e32 v71, 0
	s_waitcnt vmcnt(0)
	s_and_saveexec_b64 s[14:15], s[12:13]
	s_cbranch_execz .LBB7_718
	v_lshlrev_b64 v[42:43], 11, v[18:19]
	v_lshl_add_u64 v[42:43], v[20:21], 0, v[42:43]
	v_add_co_u32_e32 v42, vcc, 0xffffd000, v42
	s_nop 1
	v_addc_co_u32_e32 v43, vcc, -1, v43, vcc
	v_mov_b64_e32 v[42:43], v[216:217]
	v_mov_b64_e32 v[44:45], v[218:219]
	v_lshlrev_b32_e32 v68, 16, v42
	v_and_b32_e32 v69, 0xffff0000, v42
	v_lshlrev_b32_e32 v70, 16, v43
	v_and_b32_e32 v71, 0xffff0000, v43
	v_lshlrev_b32_e32 v62, 16, v44
	v_and_b32_e32 v63, 0xffff0000, v44
	v_lshlrev_b32_e32 v64, 16, v45
	v_and_b32_e32 v65, 0xffff0000, v45
.LBB7_718:
	s_or_b64 exec, exec, s[14:15]
	v_mov_b32_e32 v72, 0
	v_mov_b32_e32 v74, 0
	v_mov_b32_e32 v75, 0
	v_mov_b32_e32 v76, 0
	v_mov_b32_e32 v77, 0
	v_mov_b32_e32 v90, 0
	v_mov_b32_e32 v91, 0
	v_mov_b32_e32 v92, 0
	v_mov_b32_e32 v93, 0
	s_and_saveexec_b64 s[14:15], s[12:13]
	s_cbranch_execz .LBB7_720
	v_lshlrev_b64 v[42:43], 11, v[18:19]
	v_lshl_add_u64 v[42:43], v[20:21], 0, v[42:43]
	v_add_co_u32_e32 v42, vcc, 0xffffd000, v42
	s_nop 1
	v_addc_co_u32_e32 v43, vcc, -1, v43, vcc
	v_mov_b64_e32 v[42:43], v[220:221]
	v_mov_b64_e32 v[44:45], v[222:223]
	v_lshlrev_b32_e32 v90, 16, v42
	v_and_b32_e32 v91, 0xffff0000, v42
	v_lshlrev_b32_e32 v92, 16, v43
	v_and_b32_e32 v93, 0xffff0000, v43
	v_lshlrev_b32_e32 v74, 16, v44
	v_and_b32_e32 v75, 0xffff0000, v44
	v_lshlrev_b32_e32 v76, 16, v45
	v_and_b32_e32 v77, 0xffff0000, v45
.LBB7_720:
	s_or_b64 exec, exec, s[14:15]
	v_mov_b32_e32 v73, 0
	v_mov_b32_e32 v94, 0
	v_mov_b32_e32 v95, 0
	v_mov_b32_e32 v96, 0
	v_mov_b32_e32 v97, 0
	v_mov_b32_e32 v102, 0
	v_mov_b32_e32 v103, 0
	s_and_saveexec_b64 s[14:15], s[12:13]
	s_cbranch_execz .LBB7_722
	v_lshlrev_b64 v[42:43], 11, v[18:19]
	v_lshl_add_u64 v[42:43], v[20:21], 0, v[42:43]
	v_add_co_u32_e32 v42, vcc, 0xffffe000, v42
	s_nop 1
	v_addc_co_u32_e32 v43, vcc, -1, v43, vcc
	v_mov_b64_e32 v[42:43], v[224:225]
	v_mov_b64_e32 v[44:45], v[226:227]
	v_lshlrev_b32_e32 v96, 16, v42
	v_and_b32_e32 v97, 0xffff0000, v42
	v_lshlrev_b32_e32 v102, 16, v43
	v_and_b32_e32 v103, 0xffff0000, v43
	v_lshlrev_b32_e32 v72, 16, v44
	v_and_b32_e32 v73, 0xffff0000, v44
	v_lshlrev_b32_e32 v94, 16, v45
	v_and_b32_e32 v95, 0xffff0000, v45
.LBB7_722:
	s_or_b64 exec, exec, s[14:15]
	v_cmp_ne_u32_e32 vcc, 0, v207
	s_and_b64 s[12:13], vcc, s[40:41]
	v_mov_b32_e32 v180, 0
	v_mov_b32_e32 v106, 0
	v_mov_b32_e32 v107, 0
	v_mov_b32_e32 v108, 0
	v_mov_b32_e32 v109, 0
	v_mov_b32_e32 v104, 0
	v_mov_b32_e32 v105, 0
	v_mov_b32_e32 v182, 0
	v_mov_b32_e32 v183, 0
	s_and_saveexec_b64 s[14:15], s[12:13]
	s_cbranch_execz .LBB7_724
	v_lshlrev_b64 v[42:43], 11, v[18:19]
	v_lshl_add_u64 v[42:43], v[20:21], 0, v[42:43]
	v_add_co_u32_e32 v42, vcc, 0xffffe000, v42
	s_nop 1
	v_addc_co_u32_e32 v43, vcc, -1, v43, vcc
	v_mov_b64_e32 v[42:43], v[228:229]
	v_mov_b64_e32 v[44:45], v[230:231]
	v_lshlrev_b32_e32 v104, 16, v42
	v_and_b32_e32 v105, 0xffff0000, v42
	v_lshlrev_b32_e32 v182, 16, v43
	v_and_b32_e32 v183, 0xffff0000, v43
	v_lshlrev_b32_e32 v106, 16, v44
	v_and_b32_e32 v107, 0xffff0000, v44
	v_lshlrev_b32_e32 v108, 16, v45
	v_and_b32_e32 v109, 0xffff0000, v45
.LBB7_724:
	s_or_b64 exec, exec, s[14:15]
	v_mov_b32_e32 v181, 0
	v_mov_b32_e32 v184, 0
	v_mov_b32_e32 v185, 0
	v_mov_b32_e32 v188, 0
	v_mov_b32_e32 v189, 0
	v_mov_b32_e32 v190, 0
	v_mov_b32_e32 v191, 0
	s_and_saveexec_b64 s[14:15], s[12:13]
	s_cbranch_execz .LBB7_726
	v_lshlrev_b64 v[42:43], 11, v[18:19]
	v_lshl_add_u64 v[42:43], v[20:21], 0, v[42:43]
	v_add_co_u32_e32 v42, vcc, 0xfffff000, v42
	s_nop 1
	v_addc_co_u32_e32 v43, vcc, -1, v43, vcc
	v_mov_b64_e32 v[42:43], v[232:233]
	v_mov_b64_e32 v[44:45], v[234:235]
	v_lshlrev_b32_e32 v188, 16, v42
	v_and_b32_e32 v189, 0xffff0000, v42
	v_lshlrev_b32_e32 v190, 16, v43
	v_and_b32_e32 v191, 0xffff0000, v43
	v_lshlrev_b32_e32 v180, 16, v44
	v_and_b32_e32 v181, 0xffff0000, v44
	v_lshlrev_b32_e32 v184, 16, v45
	v_and_b32_e32 v185, 0xffff0000, v45
.LBB7_726:
	s_or_b64 exec, exec, s[14:15]
	v_cmp_ne_u32_e32 vcc, 0, v206
	v_mov_b32_e32 v66, 0
	v_mov_b32_e32 v194, 0
	v_mov_b32_e32 v195, 0
	v_mov_b32_e32 v192, 0
	v_mov_b32_e32 v193, 0
	v_mov_b32_e32 v196, 0
	v_mov_b32_e32 v197, 0
	v_mov_b32_e32 v198, 0
	v_mov_b32_e32 v199, 0
	s_and_saveexec_b64 s[12:13], vcc
	s_cbranch_execz .LBB7_728
	v_lshlrev_b64 v[42:43], 11, v[18:19]
	v_lshl_add_u64 v[42:43], v[20:21], 0, v[42:43]
	v_mov_b64_e32 v[42:43], v[236:237]
	v_mov_b64_e32 v[44:45], v[238:239]
	v_lshlrev_b32_e32 v196, 16, v42
	v_and_b32_e32 v197, 0xffff0000, v42
	v_lshlrev_b32_e32 v198, 16, v43
	v_and_b32_e32 v199, 0xffff0000, v43
	v_lshlrev_b32_e32 v194, 16, v44
	v_and_b32_e32 v195, 0xffff0000, v44
	v_lshlrev_b32_e32 v192, 16, v45
	v_and_b32_e32 v193, 0xffff0000, v45
.LBB7_728:
	s_or_b64 exec, exec, s[12:13]
	v_mov_b32_e32 v67, 0
	v_mov_b32_e32 v138, 0
	v_mov_b32_e32 v139, 0
	v_mov_b32_e32 v140, 0
	v_mov_b32_e32 v141, 0
	v_mov_b32_e32 v178, 0
	v_mov_b32_e32 v179, 0
	s_and_saveexec_b64 s[12:13], vcc
	s_cbranch_execz .LBB7_730
	v_lshlrev_b64 v[42:43], 11, v[18:19]
	v_lshl_add_u64 v[42:43], v[20:21], 0, v[42:43]
	v_mov_b64_e32 v[42:43], v[240:241]
	v_mov_b64_e32 v[44:45], v[242:243]
	v_lshlrev_b32_e32 v140, 16, v42
	v_and_b32_e32 v141, 0xffff0000, v42
	v_lshlrev_b32_e32 v178, 16, v43
	v_and_b32_e32 v179, 0xffff0000, v43
	v_lshlrev_b32_e32 v66, 16, v44
	v_and_b32_e32 v67, 0xffff0000, v44
	v_lshlrev_b32_e32 v138, 16, v45
	v_and_b32_e32 v139, 0xffff0000, v45
